# one static s_setprio 1 for waves 4-7 over the attention phase (reset to 0 at phase end)
# baseline (speedup 1.0000x reference)
.LBB0_366:
	s_mov_b32 s4, s33
	s_waitcnt lgkmcnt(0)
	s_waitcnt lgkmcnt(0)
	s_barrier
	s_cmp_lt_u32 s33, 4
	s_cbranch_scc1 .Lattn_prio_skip
	s_setprio 1
.Lattn_prio_skip:
	s_lshl_b32 s54, s4, 6
	s_mov_b32 s4, -1
	s_mov_b32 s56, s2
	v_mbcnt_lo_u32_b32 v0, s4, 0
	v_mbcnt_hi_u32_b32 v0, s4, v0
	v_add_u32_e32 v0, s54, v0
	s_mov_b32 s55, s3
	s_and_b32 s4, s55, 7
	s_cmp_lg_u32 s4, 0
	s_mov_b32 s57, 0
	s_cbranch_scc1 .LBB0_368
	s_ashr_i32 s5, s56, 31
	s_lshr_b32 s5, s5, 29
	s_add_i32 s5, s56, s5
	s_ashr_i32 s6, s5, 3
	s_and_b32 s5, s5, -8
	s_ashr_i32 s4, s55, 3
	s_sub_i32 s5, s56, s5
	s_mul_i32 s4, s5, s4
	s_add_i32 s56, s4, s6

.LBB0_561:
	s_setprio 0
	s_mov_b64 s[6:7], s[0:1]
	s_getreg_b32 s8, hwreg(HW_REG_XCC_ID, 0, 4)
	s_waitcnt vmcnt(0)
	s_barrier
	s_and_saveexec_b64 s[4:5], s[10:11]
	s_cbranch_execz .LBB0_613
	s_add_i32 s9, 0, 0x20160
	v_mov_b32_e32 v0, s9
	s_load_dwordx2 s[6:7], s[6:7], 0x80
	s_waitcnt vmcnt(0) expcnt(0) lgkmcnt(0)
	ds_read_b32 v2, v0
	s_add_i32 s9, 0, 0x20164
	v_mov_b32_e32 v0, s9
	ds_read_b32 v0, v0
	s_and_b32 s54, s8, 15
	s_waitcnt lgkmcnt(1)
	v_cmp_ne_u32_e32 vcc, 0, v2
	s_cbranch_vccnz .LBB0_577
	s_load_dwordx2 s[16:17], s[14:15], 0x4
	s_add_u32 s8, s6, 0x4200
	s_addc_u32 s9, s7, 0
	s_add_u32 s12, s6, 0x4400
	s_addc_u32 s13, s7, 0
	s_waitcnt lgkmcnt(0)
	s_mul_i32 s55, s16, s3
	s_add_u32 s16, s6, 0x4500
	s_mul_i32 s55, s55, s17
	s_addc_u32 s17, s7, 0
	s_add_u32 s18, s6, 0x4600
	s_addc_u32 s19, s7, 0
	s_add_u32 s20, s6, 0x4700
	s_addc_u32 s21, s7, 0
	s_add_u32 s22, s6, 0x4800
	s_addc_u32 s23, s7, 0
	s_add_u32 s24, s6, 0x4900
	s_addc_u32 s25, s7, 0
	s_add_u32 s26, s6, 0x4a00
	s_addc_u32 s27, s7, 0
	s_add_u32 s28, s6, 0x4b00
	s_addc_u32 s29, s7, 0
	s_add_u32 s30, s6, 0x4c00
	s_addc_u32 s31, s7, 0
	s_add_u32 s34, s6, 0x4d00
	s_addc_u32 s35, s7, 0
	s_add_u32 s36, s6, 0x4e00
	s_addc_u32 s37, s7, 0
	s_add_u32 s38, s6, 0x4f00
	s_addc_u32 s39, s7, 0
	s_add_u32 s40, s6, 0x5000
	s_addc_u32 s41, s7, 0
	s_add_u32 s42, s6, 0x5100
	s_addc_u32 s43, s7, 0
	s_add_u32 s44, s6, 0x5200
	s_addc_u32 s45, s7, 0
	s_add_u32 s46, s6, 0x5300
	s_addc_u32 s47, s7, 0
	s_mov_b32 s56, 1
	v_mov_b32_e32 v16, 0
	s_branch .LBB0_565
